# NSA selected-tile loop head: selection mask row kept in registers and both LIST reads issued together, three serial LDS round trips per tile reduced to one
# speedup vs baseline: 1.0048x; 1.0048x over previous
; #define LAS __attribute__((address_space(3)))
; template <int MODE>
; DI void nsa_tile(LAS const unsigned char* buf, const bf16x8 (&qf)[4], f32x16 (&o)[2], float& m, float& l, int kbase0, int t, bool lanesel, float slope2, int c, int hi) {
; #pragma unroll
;     for (int sub = 0; sub < 2; ++sub) {
;         const int klo = kbase0 + 32 * sub;
;         bool full, none;
;         if (MODE == 0) { full = lanesel && (klo + 31 <= t); none = !lanesel || (klo > t); }
;         else { full = (klo + 31 <= t) && (klo >= t - 511); none = (klo > t) || (klo + 31 < t - 511); }
;         if (__all(none)) continue;
;         int dbase = t - klo - 4 * hi;
;         asm volatile("" : "+v"(dbase));
;         const float b0 = none ? -1e30f : -slope2 * (float)dbase;
;         f32x16 s;
; #pragma unroll
;         for (int i = 0; i < 16; ++i) s[i] = fmaf(slope2, (float)((i & 3) + 8 * (i >> 2)), b0);
; #pragma unroll
;         for (int st = 0; st < 4; ++st) {
;             const bf16x8 a = *(LAS const bf16x8*)(buf + (32 * sub + c) * 144 + st * 32 + hi * 16);
;             s = MFMA32(a, qf[st], s);
;         }
;         if (__any(!full && !none)) {
; #pragma unroll
;             for (int i = 0; i < 16; ++i) {
; DI void nsa_unit(const Params& p, LAS unsigned char* lds, unsigned char* ldsg, int bg, int qt, int tid) {
;     ...
;         f32x16 o[2];
; #pragma unroll
;         for (int db = 0; db < 2; ++db)
; #pragma unroll
;             for (int i = 0; i < 16; ++i) o[db][i] = 0.f;
;         float m = -1e20f, l = 0.f;
;         u32x4 rk1, rv1, rk2, rv2;
;         { const int nb = LIST[0]; rk1 = *(const u32x4*)(Ksrc + (size_t)(64 * nb) * NPROJ); rv1 = *(const u32x4*)(Vsrc + 64 * nb); }
;         *(LAS u32x4*)(lds + toff) = rk1; ST_V(lds, rv1);
;         if (nl > 1) { const int nb = LIST[1]; rk1 = *(const u32x4*)(Ksrc + (size_t)(64 * nb) * NPROJ); rv1 = *(const u32x4*)(Vsrc + 64 * nb); }
;         __syncthreads();
;         int cb = 0;
;         for (int i = 0; i < nl; ++i) {
;             const int nb = LIST[i];
;             if (i + 2 < nl) { const int nb2 = LIST[i + 2]; rk2 = *(const u32x4*)(Ksrc + (size_t)(64 * nb2) * NPROJ); rv2 = *(const u32x4*)(Vsrc + 64 * nb2); }
;             const bool lanesel = (SEL[(4 * w + qi) * 4 + (nb >> 5)] >> (nb & 31)) & 1u;
;             if (__any(lanesel))
;                 nsa_tile<0>(lds + cb * NSA_TBUF, qf, o, m, l, 64 * nb, t, lanesel, slope2, c, hi);
.LBB0_818:
	s_movk_i32 s2, 0x88
	s_cmp_lt_i32 s8, 1
	v_mul_u32_u24_e32 v15, 0x88, v68
	v_mad_u32_u24 v176, v68, s2, v168
	s_waitcnt lgkmcnt(0)
	s_barrier
	s_cbranch_scc1 .LBB0_839
	v_or_b32_e32 v10, s49, v67
	s_add_i32 s2, 0, 0x26400
	v_lshl_add_u32 v113, v10, 4, s2
	v_lshlrev_b32_e32 v10, 2, v114
	v_mov_b32_e32 v175, 0
	v_sub_u32_e32 v117, v150, v10
	v_mov_b32_e32 v153, v152
	v_mov_b32_e32 v118, 0xe0ad78ec
	v_mov_b32_e32 v252, 0xe0ad78ec
	v_mov_b32_e32 v248, 0
	s_mov_b32 s9, 0
	v_readlane_b32 s10, v234, 35
	s_mov_b32 s11, 0
	v_mov_b32_e32 v48, 0
	v_mov_b32_e32 v49, v175
	v_mov_b32_e32 v50, v175
	v_mov_b32_e32 v51, v175
	v_mov_b32_e32 v52, v175
	v_mov_b32_e32 v53, v175
	v_mov_b32_e32 v54, v175
	v_mov_b32_e32 v55, v175
	v_mov_b32_e32 v56, v175
	v_mov_b32_e32 v57, v175
	v_mov_b32_e32 v58, v175
	v_mov_b32_e32 v59, v175
	v_mov_b32_e32 v60, v175
	v_mov_b32_e32 v61, v175
	v_mov_b32_e32 v62, v175
	v_mov_b32_e32 v63, v175
	v_mov_b32_e32 v64, v175
	v_mov_b32_e32 v65, v175
	v_mov_b32_e32 v66, v175
	v_mov_b32_e32 v67, v175
	v_mov_b32_e32 v68, v175
	v_mov_b32_e32 v69, v175
	v_mov_b32_e32 v70, v175
	v_mov_b32_e32 v71, v175
	v_mov_b32_e32 v72, v175
	v_mov_b32_e32 v73, v175
	v_mov_b32_e32 v74, v175
	v_mov_b32_e32 v75, v175
	v_mov_b32_e32 v76, v175
	v_mov_b32_e32 v77, v175
	v_mov_b32_e32 v78, v175
	v_mov_b32_e32 v79, v175
	ds_read_b128 v[240:243], v113
.LBB0_820:
	s_add_i32 s2, s10, -8
	v_mov_b32_e32 v80, s2
	ds_read_b32 v80, v80
	v_mov_b32_e32 v10, s10
	ds_read_b32 v10, v10
	s_add_i32 s2, s9, 2
	s_cmp_ge_i32 s2, s8
	s_waitcnt lgkmcnt(0)
	v_readfirstlane_b32 s4, v80
	s_cbranch_scc1 .LBB0_822
	v_lshlrev_b32_e32 v10, 6, v10
	v_ashrrev_i32_e32 v11, 31, v10
	v_mad_i64_i32 v[12:13], s[2:3], v10, s95, v[104:105]
	v_lshl_add_u64 v[10:11], v[10:11], 1, v[106:107]
	global_load_dwordx4 v[96:99], v[12:13], off
	s_nop 0
	global_load_dwordx4 v[10:13], v[10:11], off
.LBB0_822:
	s_ashr_i32 s2, s4, 5
	s_cmp_eq_u32 s2, 1
	s_cselect_b64 s[98:99], -1, 0
	v_cndmask_b32_e64 v80, v240, v241, s[98:99]
	s_cmp_eq_u32 s2, 2
	s_cselect_b64 s[100:101], -1, 0
	v_cndmask_b32_e64 v80, v80, v242, s[100:101]
	s_cmp_eq_u32 s2, 3
	s_cselect_b64 s[98:99], -1, 0
	v_cndmask_b32_e64 v80, v80, v243, s[98:99]
	s_and_b32 s2, s4, 31
	v_lshrrev_b32_e32 v81, s4, v80
	v_bfe_u32 v80, v80, s2, 1
	v_and_b32_e32 v81, 1, v81
	v_cmp_ne_u32_e32 vcc, 0, v80
	v_cmp_eq_u32_e64 s[2:3], 1, v81
	s_cbranch_vccz .LBB0_835
	s_lshl_b32 s15, s4, 6
	s_xor_b64 s[6:7], s[2:3], -1
	v_cmp_gt_i32_e32 vcc, s15, v150
	s_mul_i32 s5, s11, 0x4600
	s_or_b64 vcc, vcc, s[6:7]
	s_add_i32 s14, s5, 0
	v_add_u32_e32 v80, s14, v0
	s_mov_b64 s[4:5], vcc
	s_cmp_eq_u64 s[4:5], exec
	v_add_u32_e32 v119, v80, v171
	s_cbranch_scc1 .LBB0_829
	v_subrev_u32_e32 v120, s15, v117
	ds_read_b128 v[122:125], v119
	ds_read_b128 v[200:203], v119 offset:32
	ds_read_b128 v[204:207], v119 offset:64
	ds_read_b128 v[208:211], v119 offset:96
	v_cvt_f32_i32_e32 v80, v120
	s_or_b32 s4, s15, 31
	v_cmp_gt_i32_e64 s[4:5], s4, v150
	s_or_b64 s[4:5], s[6:7], s[4:5]
	v_mul_f32_e64 v80, -v152, v80
	v_cndmask_b32_e32 v94, v80, v164, vcc
	v_sub_f32_e32 v94, v94, v248
	v_fma_f32 v80, 0, v152, v94
	v_add_f32_e32 v81, v152, v94
	v_pk_fma_f32 v[82:83], v[152:153], s[72:73], v[94:95] op_sel_hi:[1,1,0]
	v_pk_fma_f32 v[84:85], v[152:153], s[74:75], v[94:95] op_sel_hi:[1,1,0]
	v_pk_fma_f32 v[86:87], v[152:153], s[76:77], v[94:95] op_sel_hi:[1,1,0]
	v_pk_fma_f32 v[88:89], v[152:153], s[70:71], v[94:95] op_sel_hi:[1,1,0]
	v_pk_fma_f32 v[90:91], v[152:153], s[78:79], v[94:95] op_sel_hi:[1,1,0]
	v_pk_fma_f32 v[92:93], v[152:153], s[80:81], v[94:95] op_sel_hi:[1,1,0]
	v_pk_fma_f32 v[94:95], v[152:153], s[82:83], v[94:95] op_sel_hi:[1,1,0]
	s_xor_b64 s[4:5], vcc, s[4:5]
	s_waitcnt lgkmcnt(3)
	v_mfma_f32_32x32x16_bf16 v[80:95], v[122:125], v[128:131], v[80:95]
	s_waitcnt lgkmcnt(2)
	v_mfma_f32_32x32x16_bf16 v[80:95], v[200:203], v[132:135], v[80:95]
	s_waitcnt lgkmcnt(1)
	v_mfma_f32_32x32x16_bf16 v[80:95], v[204:207], v[136:139], v[80:95]
	s_waitcnt lgkmcnt(0)
	v_mfma_f32_32x32x16_bf16 v[80:95], v[208:211], v[140:143], v[80:95]
	s_cmp_lg_u64 s[4:5], 0
	s_cbranch_scc0 .LBB0_826
	v_cmp_lt_i32_e32 vcc, -1, v120
	s_and_b64 vcc, s[2:3], vcc
	s_nop 8
	v_cndmask_b32_e32 v80, v164, v80, vcc
	v_cmp_lt_i32_e32 vcc, 0, v120
	s_and_b64 vcc, s[2:3], vcc
	s_nop 0
	v_cndmask_b32_e32 v81, v164, v81, vcc
	v_cmp_lt_i32_e32 vcc, 1, v120
	s_and_b64 vcc, s[2:3], vcc
	s_nop 0
	v_cndmask_b32_e32 v82, v164, v82, vcc
	v_cmp_lt_i32_e32 vcc, 2, v120
	s_and_b64 vcc, s[2:3], vcc
	s_nop 0
	v_cndmask_b32_e32 v83, v164, v83, vcc
	v_cmp_lt_i32_e32 vcc, 7, v120
	s_and_b64 vcc, s[2:3], vcc
	s_nop 0
	v_cndmask_b32_e32 v84, v164, v84, vcc
	v_cmp_lt_i32_e32 vcc, 8, v120
	s_and_b64 vcc, s[2:3], vcc
	s_nop 0
	v_cndmask_b32_e32 v85, v164, v85, vcc
	v_cmp_lt_i32_e32 vcc, 9, v120
	s_and_b64 vcc, s[2:3], vcc
	s_nop 0
	v_cndmask_b32_e32 v86, v164, v86, vcc
	v_cmp_lt_i32_e32 vcc, 10, v120
	s_and_b64 vcc, s[2:3], vcc
	s_nop 0
	v_cndmask_b32_e32 v87, v164, v87, vcc
	v_cmp_lt_i32_e32 vcc, 15, v120
	s_and_b64 vcc, s[2:3], vcc
	s_nop 0
	v_cndmask_b32_e32 v88, v164, v88, vcc
	v_cmp_lt_i32_e32 vcc, 16, v120
	s_and_b64 vcc, s[2:3], vcc
	s_nop 0
	v_cndmask_b32_e32 v89, v164, v89, vcc
	v_cmp_lt_i32_e32 vcc, 17, v120
	s_and_b64 vcc, s[2:3], vcc
	s_nop 0
	v_cndmask_b32_e32 v90, v164, v90, vcc
	v_cmp_lt_i32_e32 vcc, 18, v120
	s_and_b64 vcc, s[2:3], vcc
	s_nop 0
	v_cndmask_b32_e32 v91, v164, v91, vcc
	v_cmp_lt_i32_e32 vcc, 23, v120
	s_and_b64 vcc, s[2:3], vcc
	s_nop 0
	v_cndmask_b32_e32 v92, v164, v92, vcc
	v_cmp_lt_i32_e32 vcc, 24, v120
	s_and_b64 vcc, s[2:3], vcc
	s_nop 0
	v_cndmask_b32_e32 v93, v164, v93, vcc
	v_cmp_lt_i32_e32 vcc, 25, v120
	s_and_b64 vcc, s[2:3], vcc
	s_nop 0
	v_cndmask_b32_e32 v94, v164, v94, vcc
	v_cmp_lt_i32_e32 vcc, 26, v120
	s_and_b64 vcc, s[2:3], vcc
	s_nop 0
	v_cndmask_b32_e32 v95, v164, v95, vcc
